# NSA interior tiles: m/lsum ping-pong between the two halves (drops 4-6 v_mov per tile)
# baseline (speedup 1.0000x reference)
.Lnsw_keep0:
	v_cndmask_b32_e64 v174, v173, v206, s[38:39]
	v_sub_f32_e32 v80, v80, v174
	v_exp_f32_e32 v80, v80
	v_sub_f32_e32 v81, v81, v174
	v_exp_f32_e32 v81, v81
	v_add_f32_e32 v213, 0, v80
	v_sub_f32_e32 v82, v82, v174
	v_exp_f32_e32 v82, v82
	v_add_f32_e32 v213, v81, v213
	v_sub_f32_e32 v83, v83, v174
	v_exp_f32_e32 v83, v83
	v_add_f32_e32 v213, v82, v213
	v_cvt_pk_bf16_f32 v176, v80, v81
	v_sub_f32_e32 v84, v84, v174
	v_exp_f32_e32 v84, v84
	v_add_f32_e32 v213, v83, v213
	v_sub_f32_e32 v85, v85, v174
	v_exp_f32_e32 v85, v85
	v_add_f32_e32 v213, v84, v213
	v_cvt_pk_bf16_f32 v177, v82, v83
	v_sub_f32_e32 v86, v86, v174
	v_exp_f32_e32 v86, v86
	v_add_f32_e32 v213, v85, v213
	v_sub_f32_e32 v87, v87, v174
	v_exp_f32_e32 v87, v87
	v_add_f32_e32 v213, v86, v213
	v_cvt_pk_bf16_f32 v178, v84, v85
	v_sub_f32_e32 v88, v88, v174
	v_exp_f32_e32 v88, v88
	v_add_f32_e32 v213, v87, v213
	v_sub_f32_e32 v89, v89, v174
	v_exp_f32_e32 v89, v89
	v_add_f32_e32 v213, v88, v213
	v_cvt_pk_bf16_f32 v179, v86, v87
	v_sub_f32_e32 v90, v90, v174
	v_exp_f32_e32 v90, v90
	v_add_f32_e32 v213, v89, v213
	v_mfma_f32_32x32x16_bf16 v[32:47], v[64:67], v[176:179], v[32:47]
	v_mfma_f32_32x32x16_bf16 v[16:31], v[68:71], v[176:179], v[16:31]
	v_sub_f32_e32 v91, v91, v174
	v_exp_f32_e32 v91, v91
	v_add_f32_e32 v213, v90, v213
	v_cvt_pk_bf16_f32 v180, v88, v89
	v_sub_f32_e32 v92, v92, v174
	v_exp_f32_e32 v92, v92
	v_add_f32_e32 v213, v91, v213
	v_sub_f32_e32 v93, v93, v174
	v_exp_f32_e32 v93, v93
	v_add_f32_e32 v213, v92, v213
	v_cvt_pk_bf16_f32 v181, v90, v91
	v_sub_f32_e32 v94, v94, v174
	v_exp_f32_e32 v94, v94
	v_add_f32_e32 v213, v93, v213
	v_sub_f32_e32 v95, v95, v174
	v_exp_f32_e32 v95, v95
	v_add_f32_e32 v213, v94, v213
	v_cvt_pk_bf16_f32 v182, v92, v93
	v_add_f32_e32 v213, v95, v213
	v_cvt_pk_bf16_f32 v183, v94, v95
	v_fmac_f32_e32 v213, v169, v0
	s_nop 0
	v_mfma_f32_32x32x16_bf16 v[32:47], v[72:75], v[180:183], v[32:47]
	v_mfma_f32_32x32x16_bf16 v[16:31], v[76:79], v[180:183], v[16:31]
	v_max3_f32 v0, v48, v49, v50
	v_max3_f32 v2, v56, v57, v58
	v_max3_f32 v0, v0, v51, v52
	v_max3_f32 v2, v2, v59, v60
	v_max3_f32 v0, v0, v53, v54
	v_max3_f32 v2, v2, v61, v62
	v_max3_f32 v0, v0, v55, v63
	v_max_f32_e32 v0, v0, v2
	v_cndmask_b32_e64 v0, v0, v202, s[38:39]
	ds_bpermute_b32 v2, v119, v0
	s_waitcnt lgkmcnt(0)
	v_max3_f32 v167, v173, v0, v2
	v_sub_f32_e32 v0, v173, v167
	v_exp_f32_e32 v0, v0
	v_cmp_eq_f32_e32 vcc, v167, v173
	s_cmp_eq_u64 vcc, exec
	s_cbranch_scc1 .Lnsw_keep1
	v_pk_mul_f32 v[46:47], v[46:47], v[0:1] op_sel_hi:[1,0]
	v_pk_mul_f32 v[44:45], v[44:45], v[0:1] op_sel_hi:[1,0]
	v_pk_mul_f32 v[42:43], v[42:43], v[0:1] op_sel_hi:[1,0]
	v_pk_mul_f32 v[40:41], v[40:41], v[0:1] op_sel_hi:[1,0]
	v_pk_mul_f32 v[38:39], v[38:39], v[0:1] op_sel_hi:[1,0]
	v_pk_mul_f32 v[36:37], v[36:37], v[0:1] op_sel_hi:[1,0]
	v_pk_mul_f32 v[34:35], v[34:35], v[0:1] op_sel_hi:[1,0]
	v_pk_mul_f32 v[32:33], v[32:33], v[0:1] op_sel_hi:[1,0]
	v_pk_mul_f32 v[30:31], v[30:31], v[0:1] op_sel_hi:[1,0]
	v_pk_mul_f32 v[28:29], v[28:29], v[0:1] op_sel_hi:[1,0]
	v_pk_mul_f32 v[26:27], v[26:27], v[0:1] op_sel_hi:[1,0]
	v_pk_mul_f32 v[24:25], v[24:25], v[0:1] op_sel_hi:[1,0]
	v_pk_mul_f32 v[22:23], v[22:23], v[0:1] op_sel_hi:[1,0]
	v_pk_mul_f32 v[20:21], v[20:21], v[0:1] op_sel_hi:[1,0]
	v_pk_mul_f32 v[18:19], v[18:19], v[0:1] op_sel_hi:[1,0]
	v_pk_mul_f32 v[16:17], v[16:17], v[0:1] op_sel_hi:[1,0]
.Lnsw_keep1:
	v_cndmask_b32_e64 v174, v167, v206, s[38:39]
	v_sub_f32_e32 v48, v48, v174
	v_exp_f32_e32 v48, v48
	v_sub_f32_e32 v49, v49, v174
	v_exp_f32_e32 v49, v49
	v_add_f32_e32 v169, 0, v48
	v_sub_f32_e32 v50, v50, v174
	v_exp_f32_e32 v50, v50
	v_add_f32_e32 v169, v49, v169
	v_sub_f32_e32 v51, v51, v174
	v_exp_f32_e32 v51, v51
	v_add_f32_e32 v169, v50, v169
	v_cvt_pk_bf16_f32 v80, v48, v49
	v_sub_f32_e32 v52, v52, v174
	v_exp_f32_e32 v52, v52
	v_add_f32_e32 v169, v51, v169
	v_sub_f32_e32 v53, v53, v174
	v_exp_f32_e32 v53, v53
	v_add_f32_e32 v169, v52, v169
	v_cvt_pk_bf16_f32 v81, v50, v51
	v_sub_f32_e32 v54, v54, v174
	v_exp_f32_e32 v54, v54
	v_add_f32_e32 v169, v53, v169
	v_sub_f32_e32 v55, v55, v174
	v_exp_f32_e32 v55, v55
	v_add_f32_e32 v169, v54, v169
	v_cvt_pk_bf16_f32 v82, v52, v53
	v_sub_f32_e32 v56, v56, v174
	v_exp_f32_e32 v56, v56
	v_add_f32_e32 v169, v55, v169
	v_sub_f32_e32 v57, v57, v174
	v_exp_f32_e32 v57, v57
	v_add_f32_e32 v169, v56, v169
	v_cvt_pk_bf16_f32 v83, v54, v55
	v_sub_f32_e32 v58, v58, v174
	v_exp_f32_e32 v58, v58
	v_add_f32_e32 v169, v57, v169
	v_mfma_f32_32x32x16_bf16 v[32:47], v[220:223], v[80:83], v[32:47]
	v_mfma_f32_32x32x16_bf16 v[16:31], v[224:227], v[80:83], v[16:31]
	v_sub_f32_e32 v59, v59, v174
	v_exp_f32_e32 v59, v59
	v_add_f32_e32 v169, v58, v169
	v_cvt_pk_bf16_f32 v84, v56, v57
	v_sub_f32_e32 v60, v60, v174
	v_exp_f32_e32 v60, v60
	v_add_f32_e32 v169, v59, v169
	v_sub_f32_e32 v61, v61, v174
	v_exp_f32_e32 v61, v61
	v_add_f32_e32 v169, v60, v169
	v_cvt_pk_bf16_f32 v85, v58, v59
	v_sub_f32_e32 v62, v62, v174
	v_exp_f32_e32 v62, v62
	v_add_f32_e32 v169, v61, v169
	v_sub_f32_e32 v63, v63, v174
	v_exp_f32_e32 v63, v63
	v_add_f32_e32 v169, v62, v169
	v_cvt_pk_bf16_f32 v86, v60, v61
	v_add_f32_e32 v169, v63, v169
	v_cvt_pk_bf16_f32 v87, v62, v63
	v_fmac_f32_e32 v169, v213, v0
	s_nop 0
	v_mfma_f32_32x32x16_bf16 v[32:47], v[228:231], v[84:87], v[32:47]
	v_mfma_f32_32x32x16_bf16 v[16:31], v[232:235], v[84:87], v[16:31]
	s_branch .LBB0_296

.Lnsw1_keep0:
	v_sub_f32_e32 v80, v80, v173
	v_exp_f32_e32 v80, v80
	v_sub_f32_e32 v81, v81, v173
	v_exp_f32_e32 v81, v81
	v_add_f32_e32 v213, 0, v80
	v_sub_f32_e32 v82, v82, v173
	v_exp_f32_e32 v82, v82
	v_add_f32_e32 v213, v81, v213
	v_sub_f32_e32 v83, v83, v173
	v_exp_f32_e32 v83, v83
	v_add_f32_e32 v213, v82, v213
	v_cvt_pk_bf16_f32 v176, v80, v81
	v_sub_f32_e32 v84, v84, v173
	v_exp_f32_e32 v84, v84
	v_add_f32_e32 v213, v83, v213
	v_sub_f32_e32 v85, v85, v173
	v_exp_f32_e32 v85, v85
	v_add_f32_e32 v213, v84, v213
	v_cvt_pk_bf16_f32 v177, v82, v83
	v_sub_f32_e32 v86, v86, v173
	v_exp_f32_e32 v86, v86
	v_add_f32_e32 v213, v85, v213
	v_sub_f32_e32 v87, v87, v173
	v_exp_f32_e32 v87, v87
	v_add_f32_e32 v213, v86, v213
	v_cvt_pk_bf16_f32 v178, v84, v85
	v_sub_f32_e32 v88, v88, v173
	v_exp_f32_e32 v88, v88
	v_add_f32_e32 v213, v87, v213
	v_sub_f32_e32 v89, v89, v173
	v_exp_f32_e32 v89, v89
	v_add_f32_e32 v213, v88, v213
	v_cvt_pk_bf16_f32 v179, v86, v87
	v_sub_f32_e32 v90, v90, v173
	v_exp_f32_e32 v90, v90
	v_add_f32_e32 v213, v89, v213
	v_mfma_f32_32x32x16_bf16 v[32:47], v[64:67], v[176:179], v[32:47]
	v_mfma_f32_32x32x16_bf16 v[16:31], v[68:71], v[176:179], v[16:31]
	v_sub_f32_e32 v91, v91, v173
	v_exp_f32_e32 v91, v91
	v_add_f32_e32 v213, v90, v213
	v_cvt_pk_bf16_f32 v180, v88, v89
	v_sub_f32_e32 v92, v92, v173
	v_exp_f32_e32 v92, v92
	v_add_f32_e32 v213, v91, v213
	v_sub_f32_e32 v93, v93, v173
	v_exp_f32_e32 v93, v93
	v_add_f32_e32 v213, v92, v213
	v_cvt_pk_bf16_f32 v181, v90, v91
	v_sub_f32_e32 v94, v94, v173
	v_exp_f32_e32 v94, v94
	v_add_f32_e32 v213, v93, v213
	v_sub_f32_e32 v95, v95, v173
	v_exp_f32_e32 v95, v95
	v_add_f32_e32 v213, v94, v213
	v_cvt_pk_bf16_f32 v182, v92, v93
	v_add_f32_e32 v213, v95, v213
	v_cvt_pk_bf16_f32 v183, v94, v95
	v_fmac_f32_e32 v213, v169, v0
	s_nop 0
	v_mfma_f32_32x32x16_bf16 v[32:47], v[72:75], v[180:183], v[32:47]
	v_mfma_f32_32x32x16_bf16 v[16:31], v[76:79], v[180:183], v[16:31]
	v_max3_f32 v0, v48, v49, v50
	v_max3_f32 v216, v56, v57, v58
	v_max3_f32 v0, v0, v51, v52
	v_max3_f32 v216, v216, v59, v60
	v_max3_f32 v0, v0, v53, v54
	v_max3_f32 v216, v216, v61, v62
	v_max3_f32 v0, v0, v55, v63
	v_max_f32_e32 v0, v0, v216
	ds_bpermute_b32 v216, v119, v0
	s_waitcnt lgkmcnt(0)
	v_max3_f32 v168, v173, v0, v216
	v_sub_f32_e32 v0, v173, v168
	v_exp_f32_e32 v0, v0
	v_cmp_eq_f32_e32 vcc, v168, v173
	s_cmp_eq_u64 vcc, exec
	s_cbranch_scc1 .Lnsw1_keep1
	v_pk_mul_f32 v[46:47], v[46:47], v[0:1] op_sel_hi:[1,0]
	v_pk_mul_f32 v[44:45], v[44:45], v[0:1] op_sel_hi:[1,0]
	v_pk_mul_f32 v[42:43], v[42:43], v[0:1] op_sel_hi:[1,0]
	v_pk_mul_f32 v[40:41], v[40:41], v[0:1] op_sel_hi:[1,0]
	v_pk_mul_f32 v[38:39], v[38:39], v[0:1] op_sel_hi:[1,0]
	v_pk_mul_f32 v[36:37], v[36:37], v[0:1] op_sel_hi:[1,0]
	v_pk_mul_f32 v[34:35], v[34:35], v[0:1] op_sel_hi:[1,0]
	v_pk_mul_f32 v[32:33], v[32:33], v[0:1] op_sel_hi:[1,0]
	v_pk_mul_f32 v[30:31], v[30:31], v[0:1] op_sel_hi:[1,0]
	v_pk_mul_f32 v[28:29], v[28:29], v[0:1] op_sel_hi:[1,0]
	v_pk_mul_f32 v[26:27], v[26:27], v[0:1] op_sel_hi:[1,0]
	v_pk_mul_f32 v[24:25], v[24:25], v[0:1] op_sel_hi:[1,0]
	v_pk_mul_f32 v[22:23], v[22:23], v[0:1] op_sel_hi:[1,0]
	v_pk_mul_f32 v[20:21], v[20:21], v[0:1] op_sel_hi:[1,0]
	v_pk_mul_f32 v[18:19], v[18:19], v[0:1] op_sel_hi:[1,0]
	v_pk_mul_f32 v[16:17], v[16:17], v[0:1] op_sel_hi:[1,0]
.Lnsw1_keep1:
	v_sub_f32_e32 v48, v48, v168
	v_exp_f32_e32 v48, v48
	v_sub_f32_e32 v49, v49, v168
	v_exp_f32_e32 v49, v49
	v_add_f32_e32 v169, 0, v48
	v_sub_f32_e32 v50, v50, v168
	v_exp_f32_e32 v50, v50
	v_add_f32_e32 v169, v49, v169
	v_sub_f32_e32 v51, v51, v168
	v_exp_f32_e32 v51, v51
	v_add_f32_e32 v169, v50, v169
	v_cvt_pk_bf16_f32 v80, v48, v49
	v_sub_f32_e32 v52, v52, v168
	v_exp_f32_e32 v52, v52
	v_add_f32_e32 v169, v51, v169
	v_sub_f32_e32 v53, v53, v168
	v_exp_f32_e32 v53, v53
	v_add_f32_e32 v169, v52, v169
	v_cvt_pk_bf16_f32 v81, v50, v51
	v_sub_f32_e32 v54, v54, v168
	v_exp_f32_e32 v54, v54
	v_add_f32_e32 v169, v53, v169
	v_sub_f32_e32 v55, v55, v168
	v_exp_f32_e32 v55, v55
	v_add_f32_e32 v169, v54, v169
	v_cvt_pk_bf16_f32 v82, v52, v53
	v_sub_f32_e32 v56, v56, v168
	v_exp_f32_e32 v56, v56
	v_add_f32_e32 v169, v55, v169
	v_sub_f32_e32 v57, v57, v168
	v_exp_f32_e32 v57, v57
	v_add_f32_e32 v169, v56, v169
	v_cvt_pk_bf16_f32 v83, v54, v55
	v_sub_f32_e32 v58, v58, v168
	v_exp_f32_e32 v58, v58
	v_add_f32_e32 v169, v57, v169
	v_mfma_f32_32x32x16_bf16 v[32:47], v[220:223], v[80:83], v[32:47]
	v_mfma_f32_32x32x16_bf16 v[16:31], v[224:227], v[80:83], v[16:31]
	v_sub_f32_e32 v59, v59, v168
	v_exp_f32_e32 v59, v59
	v_add_f32_e32 v169, v58, v169
	v_cvt_pk_bf16_f32 v84, v56, v57
	v_sub_f32_e32 v60, v60, v168
	v_exp_f32_e32 v60, v60
	v_add_f32_e32 v169, v59, v169
	v_sub_f32_e32 v61, v61, v168
	v_exp_f32_e32 v61, v61
	v_add_f32_e32 v169, v60, v169
	v_cvt_pk_bf16_f32 v85, v58, v59
	v_sub_f32_e32 v62, v62, v168
	v_exp_f32_e32 v62, v62
	v_add_f32_e32 v169, v61, v169
	v_sub_f32_e32 v63, v63, v168
	v_exp_f32_e32 v63, v63
	v_add_f32_e32 v169, v62, v169
	v_cvt_pk_bf16_f32 v86, v60, v61
	v_add_f32_e32 v169, v63, v169
	v_cvt_pk_bf16_f32 v87, v62, v63
	v_fmac_f32_e32 v169, v213, v0
	s_nop 0
	v_mfma_f32_32x32x16_bf16 v[32:47], v[228:231], v[84:87], v[32:47]
	v_mfma_f32_32x32x16_bf16 v[16:31], v[232:235], v[84:87], v[16:31]
	s_branch .LBB0_314
